# nt also on the prologue x and p f32 loads (once-read there); final-store nt dropped (it was slower)
# speedup vs baseline: 1.0240x; 1.0023x over previous
.LBB0_63:
	v_add_co_u32_e32 v24, vcc, 0xfffff000, v6
	v_lshl_add_u64 v[20:21], s[8:9], 0, v[4:5]
	s_nop 0
	v_addc_co_u32_e32 v25, vcc, -1, v7, vcc
	v_add_co_u32_e32 v48, vcc, s11, v20
	s_waitcnt lgkmcnt(0)
	s_nop 0
	v_addc_co_u32_e32 v49, vcc, 0, v21, vcc
	global_load_dwordx4 v[16:19], v[24:25], off offset:-3072 nt
	global_load_dwordx4 v[20:23], v[24:25], off offset:-2048 nt
	global_load_dwordx4 v[24:27], v[24:25], off offset:-1024 nt
	global_load_dwordx4 v[28:31], v[6:7], off offset:-4096 nt
	global_load_dwordx4 v[32:35], v[6:7], off offset:-3072 nt
	global_load_dwordx4 v[36:39], v[6:7], off offset:-2048 nt
	global_load_dwordx4 v[40:43], v[6:7], off offset:-1024 nt
	global_load_dwordx4 v[44:47], v[6:7], off nt
	s_waitcnt vmcnt(7)
	v_cvt_pk_bf16_f32 v100, v16, v17
	v_cvt_pk_bf16_f32 v101, v18, v19
	global_store_dwordx2 v[48:49], v[100:101], off
	s_waitcnt vmcnt(7)
	v_cvt_pk_bf16_f32 v102, v20, v21
	v_cvt_pk_bf16_f32 v103, v22, v23
	global_store_dwordx2 v[48:49], v[102:103], off offset:512
	s_waitcnt vmcnt(7)
	v_cvt_pk_bf16_f32 v104, v24, v25
	v_cvt_pk_bf16_f32 v105, v26, v27
	global_store_dwordx2 v[48:49], v[104:105], off offset:1024
	s_waitcnt vmcnt(7)
	v_cvt_pk_bf16_f32 v106, v28, v29
	v_cvt_pk_bf16_f32 v107, v30, v31
	global_store_dwordx2 v[48:49], v[106:107], off offset:1536
	s_waitcnt vmcnt(7)
	v_cvt_pk_bf16_f32 v108, v32, v33
	v_cvt_pk_bf16_f32 v109, v34, v35
	global_store_dwordx2 v[48:49], v[108:109], off offset:2048
	s_waitcnt vmcnt(7)
	v_cvt_pk_bf16_f32 v110, v36, v37
	v_cvt_pk_bf16_f32 v111, v38, v39
	global_store_dwordx2 v[48:49], v[110:111], off offset:2560
	s_waitcnt vmcnt(7)
	v_cvt_pk_bf16_f32 v112, v40, v41
	v_cvt_pk_bf16_f32 v113, v42, v43
	global_store_dwordx2 v[48:49], v[112:113], off offset:3072
	v_cmp_lt_i32_e32 vcc, v10, v9
	v_mul_f32_e32 v17, v17, v17
	v_mul_f32_e32 v19, v19, v19
	v_fmac_f32_e32 v17, v16, v16
	v_fmac_f32_e32 v19, v18, v18
	v_add_f32_e32 v16, v17, v19
	v_cndmask_b32_e32 v50, v8, v10, vcc
	v_mul_f32_e32 v17, v21, v21
	v_mul_f32_e32 v18, v23, v23
	v_fmac_f32_e32 v17, v20, v20
	v_fmac_f32_e32 v18, v22, v22
	v_add_f32_e32 v17, v17, v18
	v_add_f32_e32 v16, v16, v17
	v_mul_f32_e32 v17, v25, v25
	v_mul_f32_e32 v18, v27, v27
	v_fmac_f32_e32 v17, v24, v24
	v_fmac_f32_e32 v18, v26, v26
	v_add_f32_e32 v17, v17, v18
	v_add_f32_e32 v16, v16, v17
	v_mul_f32_e32 v17, v29, v29
	v_mul_f32_e32 v18, v31, v31
	v_fmac_f32_e32 v17, v28, v28
	v_fmac_f32_e32 v18, v30, v30
	v_add_f32_e32 v17, v17, v18
	v_add_f32_e32 v16, v16, v17
	v_mul_f32_e32 v17, v33, v33
	v_mul_f32_e32 v18, v35, v35
	v_fmac_f32_e32 v17, v32, v32
	v_fmac_f32_e32 v18, v34, v34
	v_add_f32_e32 v17, v17, v18
	v_add_f32_e32 v16, v16, v17
	v_mul_f32_e32 v17, v37, v37
	v_mul_f32_e32 v18, v39, v39
	v_fmac_f32_e32 v17, v36, v36
	v_fmac_f32_e32 v18, v38, v38
	v_add_f32_e32 v17, v17, v18
	v_add_f32_e32 v16, v16, v17
	v_mul_f32_e32 v17, v41, v41
	v_mul_f32_e32 v18, v43, v43
	v_fmac_f32_e32 v17, v40, v40
	v_fmac_f32_e32 v18, v42, v42
	v_add_f32_e32 v17, v17, v18
	v_add_f32_e32 v16, v16, v17
	s_waitcnt vmcnt(7)
	v_mul_f32_e32 v17, v45, v45
	v_mul_f32_e32 v18, v47, v47
	v_fmac_f32_e32 v17, v44, v44
	v_fmac_f32_e32 v18, v46, v46
	v_add_f32_e32 v17, v17, v18
	v_lshlrev_b32_e32 v50, 2, v50
	v_add_f32_e32 v16, v16, v17
	ds_bpermute_b32 v17, v50, v16
	v_cmp_lt_i32_e32 vcc, v11, v9
	s_waitcnt lgkmcnt(0)
	v_add_f32_e32 v16, v16, v17
	v_cndmask_b32_e32 v18, v8, v11, vcc
	v_lshlrev_b32_e32 v18, 2, v18
	ds_bpermute_b32 v17, v18, v16
	v_cmp_lt_i32_e32 vcc, v12, v9
	s_waitcnt lgkmcnt(0)
	v_add_f32_e32 v16, v16, v17
	v_cndmask_b32_e32 v18, v8, v12, vcc
	v_lshlrev_b32_e32 v18, 2, v18
	ds_bpermute_b32 v17, v18, v16
	v_cmp_lt_i32_e32 vcc, v13, v9
	s_waitcnt lgkmcnt(0)
	v_add_f32_e32 v16, v16, v17
	v_cndmask_b32_e32 v18, v8, v13, vcc
	v_lshlrev_b32_e32 v18, 2, v18
	ds_bpermute_b32 v17, v18, v16
	v_cmp_lt_i32_e32 vcc, v14, v9
	s_waitcnt lgkmcnt(0)
	v_add_f32_e32 v16, v16, v17
	v_cndmask_b32_e32 v18, v8, v14, vcc
	v_lshlrev_b32_e32 v18, 2, v18
	ds_bpermute_b32 v17, v18, v16
	v_cmp_lt_i32_e32 vcc, v15, v9
	s_waitcnt lgkmcnt(0)
	v_add_f32_e32 v16, v16, v17
	v_cndmask_b32_e32 v18, v8, v15, vcc
	v_lshlrev_b32_e32 v17, 2, v18
	ds_bpermute_b32 v17, v17, v16
	v_cvt_pk_bf16_f32 v18, v44, v45
	v_cvt_pk_bf16_f32 v19, v46, v47
	global_store_dwordx2 v[48:49], v[18:19], off offset:3584
	s_and_saveexec_b64 s[20:21], s[4:5]
	s_cbranch_execz .LBB0_62
	s_waitcnt lgkmcnt(0)
	v_add_f32_e32 v16, v16, v17
	v_cndmask_b32_e64 v18, 0, v16, s[6:7]
	v_lshl_add_u64 v[16:17], s[8:9], 0, v[2:3]
	global_store_dword v[16:17], v18, off
	s_branch .LBB0_62
.LBB0_65:
	v_lshl_add_u32 v2, s2, 9, v69
	s_mov_b32 s4, 0x100000
	s_mov_b64 s[6:7], s[0:1]
	v_cmp_gt_i32_e32 vcc, s4, v2
	s_and_saveexec_b64 s[4:5], vcc
	s_cbranch_execz .LBB0_68
	s_load_dwordx2 s[6:7], s[6:7], 0x8
	s_waitcnt lgkmcnt(0)
	s_add_u32 s10, s8, 0x800000
	s_addc_u32 s11, s9, 0
	s_lshl_b32 s14, s42, 9
	s_mov_b64 s[12:13], 0
	s_mov_b32 s15, 0xfffff
	v_mov_b32_e32 v4, v2
	s_cmp_lg_u32 s42, 0x100
	s_cbranch_scc1 .LBB0_67
	v_lshlrev_b32_e32 v132, 4, v4
	v_lshlrev_b32_e32 v133, 3, v4
	global_load_dwordx4 v[100:103], v132, s[6:7] nt
	v_add_u32_e32 v134, 0x200000, v132
	global_load_dwordx4 v[104:107], v134, s[6:7] nt
	v_add_u32_e32 v134, 0x400000, v132
	global_load_dwordx4 v[108:111], v134, s[6:7] nt
	v_add_u32_e32 v134, 0x600000, v132
	global_load_dwordx4 v[112:115], v134, s[6:7] nt
	v_add_u32_e32 v134, 0x800000, v132
	global_load_dwordx4 v[116:119], v134, s[6:7] nt
	v_add_u32_e32 v134, 0xa00000, v132
	global_load_dwordx4 v[120:123], v134, s[6:7] nt
	v_add_u32_e32 v134, 0xc00000, v132
	global_load_dwordx4 v[124:127], v134, s[6:7] nt
	v_add_u32_e32 v134, 0xe00000, v132
	global_load_dwordx4 v[128:131], v134, s[6:7] nt
	s_waitcnt vmcnt(7)
	v_cvt_pk_bf16_f32 v136, v100, v101
	v_cvt_pk_bf16_f32 v137, v102, v103
	global_store_dwordx2 v133, v[136:137], s[10:11]
	s_waitcnt vmcnt(7)
	v_cvt_pk_bf16_f32 v138, v104, v105
	v_cvt_pk_bf16_f32 v139, v106, v107
	v_add_u32_e32 v135, 0x100000, v133
	global_store_dwordx2 v135, v[138:139], s[10:11]
	s_waitcnt vmcnt(7)
	v_cvt_pk_bf16_f32 v140, v108, v109
	v_cvt_pk_bf16_f32 v141, v110, v111
	v_add_u32_e32 v135, 0x200000, v133
	global_store_dwordx2 v135, v[140:141], s[10:11]
	s_waitcnt vmcnt(7)
	v_cvt_pk_bf16_f32 v142, v112, v113
	v_cvt_pk_bf16_f32 v143, v114, v115
	v_add_u32_e32 v135, 0x300000, v133
	global_store_dwordx2 v135, v[142:143], s[10:11]
	s_waitcnt vmcnt(7)
	v_cvt_pk_bf16_f32 v144, v116, v117
	v_cvt_pk_bf16_f32 v145, v118, v119
	v_add_u32_e32 v135, 0x400000, v133
	global_store_dwordx2 v135, v[144:145], s[10:11]
	s_waitcnt vmcnt(7)
	v_cvt_pk_bf16_f32 v146, v120, v121
	v_cvt_pk_bf16_f32 v147, v122, v123
	v_add_u32_e32 v135, 0x500000, v133
	global_store_dwordx2 v135, v[146:147], s[10:11]
	s_waitcnt vmcnt(7)
	v_cvt_pk_bf16_f32 v148, v124, v125
	v_cvt_pk_bf16_f32 v149, v126, v127
	v_add_u32_e32 v135, 0x600000, v133
	global_store_dwordx2 v135, v[148:149], s[10:11]
	s_waitcnt vmcnt(7)
	v_cvt_pk_bf16_f32 v150, v128, v129
	v_cvt_pk_bf16_f32 v151, v130, v131
	v_add_u32_e32 v135, 0x700000, v133
	global_store_dwordx2 v135, v[150:151], s[10:11]
	s_branch .LBB0_68
